# mixer work queue split per XCD (block id & 7): items sharing K/V or q/k streams pop on the same XCD
# speedup vs baseline: 1.0054x; 1.0054x over previous
.LBB0_521:
	s_mov_b32 s0, s93
	v_readlane_b32 s4, v253, 54
	v_mbcnt_lo_u32_b32 v0, -1, s0
	v_mbcnt_hi_u32_b32 v0, -1, v0
	v_or_b32_e32 v0, s84, v0
	s_mov_b32 s0, s88
	v_readlane_b32 s6, v253, 56
	v_readlane_b32 s0, v254, 52
	v_readlane_b32 s8, v253, 58
	v_readlane_b32 s1, v254, 53
	s_lshl_b32 s92, s0, 6
	s_mov_b32 s8, s0
	s_lshl_b64 s[0:1], s[92:93], 2
	v_readlane_b32 s6, v253, 20
	v_readlane_b32 s62, v253, 0
	s_add_u32 s66, s6, s0
	v_readlane_b32 s0, v253, 21
	v_readlane_b32 s63, v253, 1
	s_addc_u32 s67, s0, s1
	s_and_b32 s0, s88, 7
	s_lshl_b32 s0, s0, 8
	s_mul_i32 s1, s8, 0x700
	s_add_i32 s0, s0, s1
	s_add_i32 s0, s0, 0xf000
	s_add_u32 s66, s66, s0
	s_addc_u32 s67, s67, 0
	s_add_u32 s40, s62, 0x18b00000
	s_addc_u32 s41, s63, 0
	s_add_u32 s42, s62, 0x1bb00000
	s_addc_u32 s43, s63, 0
	s_add_u32 s44, s62, 0x1ed00000
	s_addc_u32 s45, s63, 0
	s_add_u32 s48, s62, 0x3cf00000
	s_addc_u32 s49, s63, 0
	s_lshl_b32 s52, s8, 2
	s_add_u32 s53, s62, 0x2df00000
	s_addc_u32 s58, s63, 0
	s_add_u32 s59, s62, 0x30f00000
	s_addc_u32 s80, s63, 0
	s_add_u32 s81, s62, 0x200000
	s_addc_u32 s68, s63, 0
	v_readlane_b32 s5, v253, 55
	v_readlane_b32 s18, v254, 4
	v_readlane_b32 s19, v254, 5
	s_add_u32 s54, s62, 0x12b00000
	s_mov_b32 s96, 0x10000
	s_mov_b32 s91, 0x30000
	s_mov_b64 s[64:65], s[18:19]
	v_cmp_eq_u32_e64 s[4:5], 0, v0
	s_addc_u32 s55, s63, 0
	v_readlane_b32 s7, v253, 57
	v_readlane_b32 s9, v253, 59
	v_readlane_b32 s10, v253, 60
	v_readlane_b32 s11, v253, 61
	v_readlane_b32 s12, v253, 62
	v_readlane_b32 s13, v253, 63
	v_readlane_b32 s14, v254, 0
	v_readlane_b32 s15, v254, 1
	v_readlane_b32 s16, v254, 2
	v_readlane_b32 s17, v254, 3
	s_branch .LBB0_524

.LBB0_528:
	s_or_b64 exec, exec, s[6:7]
	v_mov_b32_e32 v0, s31
	s_waitcnt vmcnt(0) lgkmcnt(0)
	s_barrier
	ds_read_b32 v0, v0
	s_movk_i32 s1, 0x51f
	s_mov_b64 s[6:7], -1
	s_waitcnt lgkmcnt(0)
	s_barrier
	v_readfirstlane_b32 s0, v0
	s_and_b32 s1, s88, 7
	s_cmpk_gt_u32 s0, 0xa3
	s_cbranch_scc1 .LBB0_523
	s_cmp_lt_u32 s0, 4
	s_cbranch_scc1 .Lq_chain
	s_cmp_lt_u32 s0, 36
	s_cbranch_scc1 .Lq_lat
	s_lshl_b32 s1, s1, 6
	s_cmpk_lt_u32 s0, 0x64
	s_cselect_b32 s8, 0, 0x1c0
	s_add_i32 s0, s0, s8
	s_add_i32 s0, s0, 0xfc
	s_add_i32 s0, s0, s1
	s_branch .Lq_done
.Lq_chain:
	s_lshl_b32 s1, s1, 2
	s_add_i32 s0, s0, s1
	s_branch .Lq_done
.Lq_lat:
	s_sub_i32 s0, s0, 4
	s_lshl_b32 s1, s1, 4
	s_and_b32 s8, s0, 15
	s_or_b32 s1, s1, s8
	s_lshr_b32 s0, s0, 4
	s_lshl_b32 s0, s0, 7
	s_or_b32 s0, s0, s1
	s_add_i32 s0, s0, 32
.Lq_done:
	s_cmp_lt_i32 s0, 32
	s_cselect_b64 s[56:57], -1, 0
	s_add_i32 s1, s0, 0xfffffee0
	s_cmpk_lt_u32 s1, 0x200
	s_cselect_b64 s[6:7], -1, 0
	s_or_b64 s[6:7], s[56:57], s[6:7]
	s_andn2_b64 vcc, exec, s[6:7]
	s_mov_b64 s[6:7], -1
	s_cbranch_vccz .LBB0_555
	s_lshl_b32 s46, s0, 1
	s_cmpk_lt_u32 s0, 0x120
	s_cselect_b32 s8, 64, 0x440
	s_sub_i32 s46, s46, s8
	s_cmpk_gt_u32 s46, 0x1ff
	s_cbranch_scc1 .Lam_ctx
	s_lshr_b32 s8, s46, 8
	s_bfe_u32 s9, s46, 0x30002
	s_lshl_b32 s10, s8, 11
	s_lshl_b32 s9, s9, 8
	s_add_i32 s10, s10, s9
	s_add_i32 s10, s10, 0x2000
	s_mulk_i32 s8, 0x900
	s_add_i32 s11, s8, 0x2000
	s_bfe_u32 s12, s46, 0x30005
	s_mov_b32 s13, 36
	s_branch .Lam_go
